# phase 0 mod GEMM: all 64 w_ada operand loads of a job issued before the MFMA loop (was 8 exposed load-wait-convert rounds), loop unrolled with counted waits
# speedup vs baseline: 1.0549x; 1.0048x over previous
.LBB0_64:
	v_lshl_add_u64 v[80:81], v[92:93], 0, s[0:1]
	global_load_dword v151, v[80:81], off
	v_add_co_u32_e32 v82, vcc, s6, v80
	s_nop 1
	v_addc_co_u32_e32 v83, vcc, 0, v81, vcc
	global_load_dword v152, v[82:83], off
	v_add_co_u32_e32 v82, vcc, s11, v80
	s_nop 1
	v_addc_co_u32_e32 v83, vcc, 0, v81, vcc
	global_load_dword v153, v[82:83], off
	v_add_co_u32_e32 v82, vcc, s13, v80
	s_nop 1
	v_addc_co_u32_e32 v83, vcc, 0, v81, vcc
	global_load_dword v154, v[82:83], off
	v_add_co_u32_e32 v82, vcc, s56, v80
	s_nop 1
	v_addc_co_u32_e32 v83, vcc, 0, v81, vcc
	global_load_dword v155, v[82:83], off
	v_add_co_u32_e32 v82, vcc, s57, v80
	s_nop 1
	v_addc_co_u32_e32 v83, vcc, 0, v81, vcc
	global_load_dword v156, v[82:83], off
	v_add_co_u32_e32 v82, vcc, s60, v80
	s_nop 1
	v_addc_co_u32_e32 v83, vcc, 0, v81, vcc
	global_load_dword v157, v[82:83], off
	v_add_co_u32_e32 v82, vcc, s61, v80
	s_nop 1
	v_addc_co_u32_e32 v83, vcc, 0, v81, vcc
	global_load_dword v158, v[82:83], off
	v_lshl_add_u64 v[80:81], v[90:91], 0, s[0:1]
	global_load_dword v159, v[80:81], off
	v_add_co_u32_e32 v82, vcc, s6, v80
	s_nop 1
	v_addc_co_u32_e32 v83, vcc, 0, v81, vcc
	global_load_dword v160, v[82:83], off
	v_add_co_u32_e32 v82, vcc, s11, v80
	s_nop 1
	v_addc_co_u32_e32 v83, vcc, 0, v81, vcc
	global_load_dword v161, v[82:83], off
	v_add_co_u32_e32 v82, vcc, s13, v80
	s_nop 1
	v_addc_co_u32_e32 v83, vcc, 0, v81, vcc
	global_load_dword v162, v[82:83], off
	v_add_co_u32_e32 v82, vcc, s56, v80
	s_nop 1
	v_addc_co_u32_e32 v83, vcc, 0, v81, vcc
	global_load_dword v163, v[82:83], off
	v_add_co_u32_e32 v82, vcc, s57, v80
	s_nop 1
	v_addc_co_u32_e32 v83, vcc, 0, v81, vcc
	global_load_dword v164, v[82:83], off
	v_add_co_u32_e32 v82, vcc, s60, v80
	s_nop 1
	v_addc_co_u32_e32 v83, vcc, 0, v81, vcc
	global_load_dword v165, v[82:83], off
	v_add_co_u32_e32 v82, vcc, s61, v80
	s_nop 1
	v_addc_co_u32_e32 v83, vcc, 0, v81, vcc
	global_load_dword v166, v[82:83], off
	s_add_u32 s0, s0, 0xc0000
	s_addc_u32 s1, s1, 0
	v_lshl_add_u64 v[80:81], v[92:93], 0, s[0:1]
	global_load_dword v167, v[80:81], off
	v_add_co_u32_e32 v82, vcc, s6, v80
	s_nop 1
	v_addc_co_u32_e32 v83, vcc, 0, v81, vcc
	global_load_dword v168, v[82:83], off
	v_add_co_u32_e32 v82, vcc, s11, v80
	s_nop 1
	v_addc_co_u32_e32 v83, vcc, 0, v81, vcc
	global_load_dword v169, v[82:83], off
	v_add_co_u32_e32 v82, vcc, s13, v80
	s_nop 1
	v_addc_co_u32_e32 v83, vcc, 0, v81, vcc
	global_load_dword v170, v[82:83], off
	v_add_co_u32_e32 v82, vcc, s56, v80
	s_nop 1
	v_addc_co_u32_e32 v83, vcc, 0, v81, vcc
	global_load_dword v171, v[82:83], off
	v_add_co_u32_e32 v82, vcc, s57, v80
	s_nop 1
	v_addc_co_u32_e32 v83, vcc, 0, v81, vcc
	global_load_dword v172, v[82:83], off
	v_add_co_u32_e32 v82, vcc, s60, v80
	s_nop 1
	v_addc_co_u32_e32 v83, vcc, 0, v81, vcc
	global_load_dword v173, v[82:83], off
	v_add_co_u32_e32 v82, vcc, s61, v80
	s_nop 1
	v_addc_co_u32_e32 v83, vcc, 0, v81, vcc
	global_load_dword v174, v[82:83], off
	v_lshl_add_u64 v[80:81], v[90:91], 0, s[0:1]
	global_load_dword v175, v[80:81], off
	v_add_co_u32_e32 v82, vcc, s6, v80
	s_nop 1
	v_addc_co_u32_e32 v83, vcc, 0, v81, vcc
	global_load_dword v176, v[82:83], off
	v_add_co_u32_e32 v82, vcc, s11, v80
	s_nop 1
	v_addc_co_u32_e32 v83, vcc, 0, v81, vcc
	global_load_dword v177, v[82:83], off
	v_add_co_u32_e32 v82, vcc, s13, v80
	s_nop 1
	v_addc_co_u32_e32 v83, vcc, 0, v81, vcc
	global_load_dword v178, v[82:83], off
	v_add_co_u32_e32 v82, vcc, s56, v80
	s_nop 1
	v_addc_co_u32_e32 v83, vcc, 0, v81, vcc
	global_load_dword v179, v[82:83], off
	v_add_co_u32_e32 v82, vcc, s57, v80
	s_nop 1
	v_addc_co_u32_e32 v83, vcc, 0, v81, vcc
	global_load_dword v180, v[82:83], off
	v_add_co_u32_e32 v82, vcc, s60, v80
	s_nop 1
	v_addc_co_u32_e32 v83, vcc, 0, v81, vcc
	global_load_dword v181, v[82:83], off
	v_add_co_u32_e32 v82, vcc, s61, v80
	s_nop 1
	v_addc_co_u32_e32 v83, vcc, 0, v81, vcc
	global_load_dword v182, v[82:83], off
	s_add_u32 s0, s0, 0xc0000
	s_addc_u32 s1, s1, 0
	v_lshl_add_u64 v[80:81], v[92:93], 0, s[0:1]
	global_load_dword v183, v[80:81], off
	v_add_co_u32_e32 v82, vcc, s6, v80
	s_nop 1
	v_addc_co_u32_e32 v83, vcc, 0, v81, vcc
	global_load_dword v184, v[82:83], off
	v_add_co_u32_e32 v82, vcc, s11, v80
	s_nop 1
	v_addc_co_u32_e32 v83, vcc, 0, v81, vcc
	global_load_dword v185, v[82:83], off
	v_add_co_u32_e32 v82, vcc, s13, v80
	s_nop 1
	v_addc_co_u32_e32 v83, vcc, 0, v81, vcc
	global_load_dword v186, v[82:83], off
	v_add_co_u32_e32 v82, vcc, s56, v80
	s_nop 1
	v_addc_co_u32_e32 v83, vcc, 0, v81, vcc
	global_load_dword v187, v[82:83], off
	v_add_co_u32_e32 v82, vcc, s57, v80
	s_nop 1
	v_addc_co_u32_e32 v83, vcc, 0, v81, vcc
	global_load_dword v188, v[82:83], off
	v_add_co_u32_e32 v82, vcc, s60, v80
	s_nop 1
	v_addc_co_u32_e32 v83, vcc, 0, v81, vcc
	global_load_dword v189, v[82:83], off
	v_add_co_u32_e32 v82, vcc, s61, v80
	s_nop 1
	v_addc_co_u32_e32 v83, vcc, 0, v81, vcc
	global_load_dword v190, v[82:83], off
	v_lshl_add_u64 v[80:81], v[90:91], 0, s[0:1]
	global_load_dword v220, v[80:81], off
	v_add_co_u32_e32 v82, vcc, s6, v80
	s_nop 1
	v_addc_co_u32_e32 v83, vcc, 0, v81, vcc
	global_load_dword v221, v[82:83], off
	v_add_co_u32_e32 v82, vcc, s11, v80
	s_nop 1
	v_addc_co_u32_e32 v83, vcc, 0, v81, vcc
	global_load_dword v222, v[82:83], off
	v_add_co_u32_e32 v82, vcc, s13, v80
	s_nop 1
	v_addc_co_u32_e32 v83, vcc, 0, v81, vcc
	global_load_dword v223, v[82:83], off
	v_add_co_u32_e32 v82, vcc, s56, v80
	s_nop 1
	v_addc_co_u32_e32 v83, vcc, 0, v81, vcc
	global_load_dword v224, v[82:83], off
	v_add_co_u32_e32 v82, vcc, s57, v80
	s_nop 1
	v_addc_co_u32_e32 v83, vcc, 0, v81, vcc
	global_load_dword v225, v[82:83], off
	v_add_co_u32_e32 v82, vcc, s60, v80
	s_nop 1
	v_addc_co_u32_e32 v83, vcc, 0, v81, vcc
	global_load_dword v226, v[82:83], off
	v_add_co_u32_e32 v82, vcc, s61, v80
	s_nop 1
	v_addc_co_u32_e32 v83, vcc, 0, v81, vcc
	global_load_dword v227, v[82:83], off
	s_add_u32 s0, s0, 0xc0000
	s_addc_u32 s1, s1, 0
	v_lshl_add_u64 v[80:81], v[92:93], 0, s[0:1]
	global_load_dword v228, v[80:81], off
	v_add_co_u32_e32 v82, vcc, s6, v80
	s_nop 1
	v_addc_co_u32_e32 v83, vcc, 0, v81, vcc
	global_load_dword v229, v[82:83], off
	v_add_co_u32_e32 v82, vcc, s11, v80
	s_nop 1
	v_addc_co_u32_e32 v83, vcc, 0, v81, vcc
	global_load_dword v230, v[82:83], off
	v_add_co_u32_e32 v82, vcc, s13, v80
	s_nop 1
	v_addc_co_u32_e32 v83, vcc, 0, v81, vcc
	global_load_dword v231, v[82:83], off
	v_add_co_u32_e32 v82, vcc, s56, v80
	s_nop 1
	v_addc_co_u32_e32 v83, vcc, 0, v81, vcc
	global_load_dword v232, v[82:83], off
	v_add_co_u32_e32 v82, vcc, s57, v80
	s_nop 1
	v_addc_co_u32_e32 v83, vcc, 0, v81, vcc
	global_load_dword v233, v[82:83], off
	v_add_co_u32_e32 v82, vcc, s60, v80
	s_nop 1
	v_addc_co_u32_e32 v83, vcc, 0, v81, vcc
	global_load_dword v234, v[82:83], off
	v_add_co_u32_e32 v82, vcc, s61, v80
	s_nop 1
	v_addc_co_u32_e32 v83, vcc, 0, v81, vcc
	global_load_dword v239, v[82:83], off
	v_lshl_add_u64 v[80:81], v[90:91], 0, s[0:1]
	global_load_dword v240, v[80:81], off
	v_add_co_u32_e32 v82, vcc, s6, v80
	s_nop 1
	v_addc_co_u32_e32 v83, vcc, 0, v81, vcc
	global_load_dword v241, v[82:83], off
	v_add_co_u32_e32 v82, vcc, s11, v80
	s_nop 1
	v_addc_co_u32_e32 v83, vcc, 0, v81, vcc
	global_load_dword v242, v[82:83], off
	v_add_co_u32_e32 v82, vcc, s13, v80
	s_nop 1
	v_addc_co_u32_e32 v83, vcc, 0, v81, vcc
	global_load_dword v243, v[82:83], off
	v_add_co_u32_e32 v82, vcc, s56, v80
	s_nop 1
	v_addc_co_u32_e32 v83, vcc, 0, v81, vcc
	global_load_dword v244, v[82:83], off
	v_add_co_u32_e32 v82, vcc, s57, v80
	s_nop 1
	v_addc_co_u32_e32 v83, vcc, 0, v81, vcc
	global_load_dword v245, v[82:83], off
	v_add_co_u32_e32 v82, vcc, s60, v80
	s_nop 1
	v_addc_co_u32_e32 v83, vcc, 0, v81, vcc
	global_load_dword v246, v[82:83], off
	v_add_co_u32_e32 v82, vcc, s61, v80
	s_nop 1
	v_addc_co_u32_e32 v83, vcc, 0, v81, vcc
	global_load_dword v247, v[82:83], off
	s_add_u32 s0, s0, 0xc0000
	s_addc_u32 s1, s1, 0
	s_waitcnt vmcnt(56)
	v_bfe_u32 v120, v151, 16, 1
	v_add3_u32 v151, v151, v120, s12
	v_bfe_u32 v120, v152, 16, 1
	v_add3_u32 v152, v152, v120, s12
	v_bfe_u32 v120, v153, 16, 1
	v_add3_u32 v153, v153, v120, s12
	v_bfe_u32 v120, v154, 16, 1
	v_add3_u32 v154, v154, v120, s12
	v_bfe_u32 v120, v155, 16, 1
	v_add3_u32 v155, v155, v120, s12
	v_bfe_u32 v120, v156, 16, 1
	v_add3_u32 v156, v156, v120, s12
	v_bfe_u32 v120, v157, 16, 1
	v_add3_u32 v157, v157, v120, s12
	v_bfe_u32 v120, v158, 16, 1
	v_add3_u32 v158, v158, v120, s12
	v_perm_b32 v83, v158, v157, s62
	v_perm_b32 v82, v156, v155, s62
	v_perm_b32 v81, v154, v153, s62
	v_perm_b32 v80, v152, v151, s62
	ds_read_b128 v[108:111], v84
	ds_read_b128 v[112:115], v84 offset:8704
	s_waitcnt lgkmcnt(1)
	v_mfma_f32_32x32x16_bf16 v[64:79], v[108:111], v[80:83], v[64:79]
	ds_read_b128 v[108:111], v84 offset:17408
	s_waitcnt lgkmcnt(1)
	v_mfma_f32_32x32x16_bf16 v[48:63], v[112:115], v[80:83], v[48:63]
	ds_read_b128 v[112:115], v84 offset:26112
	s_waitcnt lgkmcnt(1)
	v_mfma_f32_32x32x16_bf16 v[32:47], v[108:111], v[80:83], v[32:47]
	ds_read_b128 v[108:111], v84 offset:34816
	s_waitcnt lgkmcnt(1)
	v_mfma_f32_32x32x16_bf16 v[16:31], v[112:115], v[80:83], v[16:31]
	s_waitcnt lgkmcnt(0)
	v_mfma_f32_32x32x16_bf16 v[0:15], v[108:111], v[80:83], v[0:15]
	s_waitcnt vmcnt(48)
	v_bfe_u32 v120, v159, 16, 1
	v_add3_u32 v159, v159, v120, s12
	v_bfe_u32 v120, v160, 16, 1
	v_add3_u32 v160, v160, v120, s12
	v_bfe_u32 v120, v161, 16, 1
	v_add3_u32 v161, v161, v120, s12
	v_bfe_u32 v120, v162, 16, 1
	v_add3_u32 v162, v162, v120, s12
	v_bfe_u32 v120, v163, 16, 1
	v_add3_u32 v163, v163, v120, s12
	v_bfe_u32 v120, v164, 16, 1
	v_add3_u32 v164, v164, v120, s12
	v_bfe_u32 v120, v165, 16, 1
	v_add3_u32 v165, v165, v120, s12
	v_bfe_u32 v120, v166, 16, 1
	v_add3_u32 v166, v166, v120, s12
	v_perm_b32 v119, v166, v165, s62
	v_perm_b32 v118, v164, v163, s62
	v_perm_b32 v117, v162, v161, s62
	v_perm_b32 v116, v160, v159, s62
	ds_read_b128 v[108:111], v84 offset:32
	ds_read_b128 v[112:115], v84 offset:8736
	s_waitcnt lgkmcnt(1)
	v_mfma_f32_32x32x16_bf16 v[64:79], v[108:111], v[116:119], v[64:79]
	ds_read_b128 v[108:111], v84 offset:17440
	s_waitcnt lgkmcnt(1)
	v_mfma_f32_32x32x16_bf16 v[48:63], v[112:115], v[116:119], v[48:63]
	ds_read_b128 v[112:115], v84 offset:26144
	s_waitcnt lgkmcnt(1)
	v_mfma_f32_32x32x16_bf16 v[32:47], v[108:111], v[116:119], v[32:47]
	ds_read_b128 v[108:111], v84 offset:34848
	s_waitcnt lgkmcnt(1)
	v_mfma_f32_32x32x16_bf16 v[16:31], v[112:115], v[116:119], v[16:31]
	s_waitcnt lgkmcnt(0)
	v_mfma_f32_32x32x16_bf16 v[0:15], v[108:111], v[116:119], v[0:15]
	s_waitcnt vmcnt(40)
	v_bfe_u32 v120, v167, 16, 1
	v_add3_u32 v167, v167, v120, s12
	v_bfe_u32 v120, v168, 16, 1
	v_add3_u32 v168, v168, v120, s12
	v_bfe_u32 v120, v169, 16, 1
	v_add3_u32 v169, v169, v120, s12
	v_bfe_u32 v120, v170, 16, 1
	v_add3_u32 v170, v170, v120, s12
	v_bfe_u32 v120, v171, 16, 1
	v_add3_u32 v171, v171, v120, s12
	v_bfe_u32 v120, v172, 16, 1
	v_add3_u32 v172, v172, v120, s12
	v_bfe_u32 v120, v173, 16, 1
	v_add3_u32 v173, v173, v120, s12
	v_bfe_u32 v120, v174, 16, 1
	v_add3_u32 v174, v174, v120, s12
	v_perm_b32 v83, v174, v173, s62
	v_perm_b32 v82, v172, v171, s62
	v_perm_b32 v81, v170, v169, s62
	v_perm_b32 v80, v168, v167, s62
	ds_read_b128 v[108:111], v84 offset:64
	ds_read_b128 v[112:115], v84 offset:8768
	s_waitcnt lgkmcnt(1)
	v_mfma_f32_32x32x16_bf16 v[64:79], v[108:111], v[80:83], v[64:79]
	ds_read_b128 v[108:111], v84 offset:17472
	s_waitcnt lgkmcnt(1)
	v_mfma_f32_32x32x16_bf16 v[48:63], v[112:115], v[80:83], v[48:63]
	ds_read_b128 v[112:115], v84 offset:26176
	s_waitcnt lgkmcnt(1)
	v_mfma_f32_32x32x16_bf16 v[32:47], v[108:111], v[80:83], v[32:47]
	ds_read_b128 v[108:111], v84 offset:34880
	s_waitcnt lgkmcnt(1)
	v_mfma_f32_32x32x16_bf16 v[16:31], v[112:115], v[80:83], v[16:31]
	s_waitcnt lgkmcnt(0)
	v_mfma_f32_32x32x16_bf16 v[0:15], v[108:111], v[80:83], v[0:15]
	s_waitcnt vmcnt(32)
	v_bfe_u32 v120, v175, 16, 1
	v_add3_u32 v175, v175, v120, s12
	v_bfe_u32 v120, v176, 16, 1
	v_add3_u32 v176, v176, v120, s12
	v_bfe_u32 v120, v177, 16, 1
	v_add3_u32 v177, v177, v120, s12
	v_bfe_u32 v120, v178, 16, 1
	v_add3_u32 v178, v178, v120, s12
	v_bfe_u32 v120, v179, 16, 1
	v_add3_u32 v179, v179, v120, s12
	v_bfe_u32 v120, v180, 16, 1
	v_add3_u32 v180, v180, v120, s12
	v_bfe_u32 v120, v181, 16, 1
	v_add3_u32 v181, v181, v120, s12
	v_bfe_u32 v120, v182, 16, 1
	v_add3_u32 v182, v182, v120, s12
	v_perm_b32 v119, v182, v181, s62
	v_perm_b32 v118, v180, v179, s62
	v_perm_b32 v117, v178, v177, s62
	v_perm_b32 v116, v176, v175, s62
	ds_read_b128 v[108:111], v84 offset:96
	ds_read_b128 v[112:115], v84 offset:8800
	s_waitcnt lgkmcnt(1)
	v_mfma_f32_32x32x16_bf16 v[64:79], v[108:111], v[116:119], v[64:79]
	ds_read_b128 v[108:111], v84 offset:17504
	s_waitcnt lgkmcnt(1)
	v_mfma_f32_32x32x16_bf16 v[48:63], v[112:115], v[116:119], v[48:63]
	ds_read_b128 v[112:115], v84 offset:26208
	s_waitcnt lgkmcnt(1)
	v_mfma_f32_32x32x16_bf16 v[32:47], v[108:111], v[116:119], v[32:47]
	ds_read_b128 v[108:111], v84 offset:34912
	s_waitcnt lgkmcnt(1)
	v_mfma_f32_32x32x16_bf16 v[16:31], v[112:115], v[116:119], v[16:31]
	s_waitcnt lgkmcnt(0)
	v_mfma_f32_32x32x16_bf16 v[0:15], v[108:111], v[116:119], v[0:15]
	s_waitcnt vmcnt(24)
	v_bfe_u32 v120, v183, 16, 1
	v_add3_u32 v183, v183, v120, s12
	v_bfe_u32 v120, v184, 16, 1
	v_add3_u32 v184, v184, v120, s12
	v_bfe_u32 v120, v185, 16, 1
	v_add3_u32 v185, v185, v120, s12
	v_bfe_u32 v120, v186, 16, 1
	v_add3_u32 v186, v186, v120, s12
	v_bfe_u32 v120, v187, 16, 1
	v_add3_u32 v187, v187, v120, s12
	v_bfe_u32 v120, v188, 16, 1
	v_add3_u32 v188, v188, v120, s12
	v_bfe_u32 v120, v189, 16, 1
	v_add3_u32 v189, v189, v120, s12
	v_bfe_u32 v120, v190, 16, 1
	v_add3_u32 v190, v190, v120, s12
	v_perm_b32 v83, v190, v189, s62
	v_perm_b32 v82, v188, v187, s62
	v_perm_b32 v81, v186, v185, s62
	v_perm_b32 v80, v184, v183, s62
	ds_read_b128 v[108:111], v84 offset:128
	ds_read_b128 v[112:115], v84 offset:8832
	s_waitcnt lgkmcnt(1)
	v_mfma_f32_32x32x16_bf16 v[64:79], v[108:111], v[80:83], v[64:79]
	ds_read_b128 v[108:111], v84 offset:17536
	s_waitcnt lgkmcnt(1)
	v_mfma_f32_32x32x16_bf16 v[48:63], v[112:115], v[80:83], v[48:63]
	ds_read_b128 v[112:115], v84 offset:26240
	s_waitcnt lgkmcnt(1)
	v_mfma_f32_32x32x16_bf16 v[32:47], v[108:111], v[80:83], v[32:47]
	ds_read_b128 v[108:111], v84 offset:34944
	s_waitcnt lgkmcnt(1)
	v_mfma_f32_32x32x16_bf16 v[16:31], v[112:115], v[80:83], v[16:31]
	s_waitcnt lgkmcnt(0)
	v_mfma_f32_32x32x16_bf16 v[0:15], v[108:111], v[80:83], v[0:15]
	s_waitcnt vmcnt(16)
	v_bfe_u32 v120, v220, 16, 1
	v_add3_u32 v220, v220, v120, s12
	v_bfe_u32 v120, v221, 16, 1
	v_add3_u32 v221, v221, v120, s12
	v_bfe_u32 v120, v222, 16, 1
	v_add3_u32 v222, v222, v120, s12
	v_bfe_u32 v120, v223, 16, 1
	v_add3_u32 v223, v223, v120, s12
	v_bfe_u32 v120, v224, 16, 1
	v_add3_u32 v224, v224, v120, s12
	v_bfe_u32 v120, v225, 16, 1
	v_add3_u32 v225, v225, v120, s12
	v_bfe_u32 v120, v226, 16, 1
	v_add3_u32 v226, v226, v120, s12
	v_bfe_u32 v120, v227, 16, 1
	v_add3_u32 v227, v227, v120, s12
	v_perm_b32 v119, v227, v226, s62
	v_perm_b32 v118, v225, v224, s62
	v_perm_b32 v117, v223, v222, s62
	v_perm_b32 v116, v221, v220, s62
	ds_read_b128 v[108:111], v84 offset:160
	ds_read_b128 v[112:115], v84 offset:8864
	s_waitcnt lgkmcnt(1)
	v_mfma_f32_32x32x16_bf16 v[64:79], v[108:111], v[116:119], v[64:79]
	ds_read_b128 v[108:111], v84 offset:17568
	s_waitcnt lgkmcnt(1)
	v_mfma_f32_32x32x16_bf16 v[48:63], v[112:115], v[116:119], v[48:63]
	ds_read_b128 v[112:115], v84 offset:26272
	s_waitcnt lgkmcnt(1)
	v_mfma_f32_32x32x16_bf16 v[32:47], v[108:111], v[116:119], v[32:47]
	ds_read_b128 v[108:111], v84 offset:34976
	s_waitcnt lgkmcnt(1)
	v_mfma_f32_32x32x16_bf16 v[16:31], v[112:115], v[116:119], v[16:31]
	s_waitcnt lgkmcnt(0)
	v_mfma_f32_32x32x16_bf16 v[0:15], v[108:111], v[116:119], v[0:15]
	s_waitcnt vmcnt(8)
	v_bfe_u32 v120, v228, 16, 1
	v_add3_u32 v228, v228, v120, s12
	v_bfe_u32 v120, v229, 16, 1
	v_add3_u32 v229, v229, v120, s12
	v_bfe_u32 v120, v230, 16, 1
	v_add3_u32 v230, v230, v120, s12
	v_bfe_u32 v120, v231, 16, 1
	v_add3_u32 v231, v231, v120, s12
	v_bfe_u32 v120, v232, 16, 1
	v_add3_u32 v232, v232, v120, s12
	v_bfe_u32 v120, v233, 16, 1
	v_add3_u32 v233, v233, v120, s12
	v_bfe_u32 v120, v234, 16, 1
	v_add3_u32 v234, v234, v120, s12
	v_bfe_u32 v120, v239, 16, 1
	v_add3_u32 v239, v239, v120, s12
	v_perm_b32 v83, v239, v234, s62
	v_perm_b32 v82, v233, v232, s62
	v_perm_b32 v81, v231, v230, s62
	v_perm_b32 v80, v229, v228, s62
	ds_read_b128 v[108:111], v84 offset:192
	ds_read_b128 v[112:115], v84 offset:8896
	s_waitcnt lgkmcnt(1)
	v_mfma_f32_32x32x16_bf16 v[64:79], v[108:111], v[80:83], v[64:79]
	ds_read_b128 v[108:111], v84 offset:17600
	s_waitcnt lgkmcnt(1)
	v_mfma_f32_32x32x16_bf16 v[48:63], v[112:115], v[80:83], v[48:63]
	ds_read_b128 v[112:115], v84 offset:26304
	s_waitcnt lgkmcnt(1)
	v_mfma_f32_32x32x16_bf16 v[32:47], v[108:111], v[80:83], v[32:47]
	ds_read_b128 v[108:111], v84 offset:35008
	s_waitcnt lgkmcnt(1)
	v_mfma_f32_32x32x16_bf16 v[16:31], v[112:115], v[80:83], v[16:31]
	s_waitcnt lgkmcnt(0)
	v_mfma_f32_32x32x16_bf16 v[0:15], v[108:111], v[80:83], v[0:15]
	s_waitcnt vmcnt(0)
	v_bfe_u32 v120, v240, 16, 1
	v_add3_u32 v240, v240, v120, s12
	v_bfe_u32 v120, v241, 16, 1
	v_add3_u32 v241, v241, v120, s12
	v_bfe_u32 v120, v242, 16, 1
	v_add3_u32 v242, v242, v120, s12
	v_bfe_u32 v120, v243, 16, 1
	v_add3_u32 v243, v243, v120, s12
	v_bfe_u32 v120, v244, 16, 1
	v_add3_u32 v244, v244, v120, s12
	v_bfe_u32 v120, v245, 16, 1
	v_add3_u32 v245, v245, v120, s12
	v_bfe_u32 v120, v246, 16, 1
	v_add3_u32 v246, v246, v120, s12
	v_bfe_u32 v120, v247, 16, 1
	v_add3_u32 v247, v247, v120, s12
	v_perm_b32 v119, v247, v246, s62
	v_perm_b32 v118, v245, v244, s62
	v_perm_b32 v117, v243, v242, s62
	v_perm_b32 v116, v241, v240, s62
	ds_read_b128 v[108:111], v84 offset:224
	ds_read_b128 v[112:115], v84 offset:8928
	s_waitcnt lgkmcnt(1)
	v_mfma_f32_32x32x16_bf16 v[64:79], v[108:111], v[116:119], v[64:79]
	ds_read_b128 v[108:111], v84 offset:17632
	s_waitcnt lgkmcnt(1)
	v_mfma_f32_32x32x16_bf16 v[48:63], v[112:115], v[116:119], v[48:63]
	ds_read_b128 v[112:115], v84 offset:26336
	s_waitcnt lgkmcnt(1)
	v_mfma_f32_32x32x16_bf16 v[32:47], v[108:111], v[116:119], v[32:47]
	ds_read_b128 v[108:111], v84 offset:35040
	s_waitcnt lgkmcnt(1)
	v_mfma_f32_32x32x16_bf16 v[16:31], v[112:115], v[116:119], v[16:31]
	s_waitcnt lgkmcnt(0)
	v_mfma_f32_32x32x16_bf16 v[0:15], v[108:111], v[116:119], v[0:15]
	v_add_u32_e32 v84, 0x100, v84
	s_lshl_b32 s0, s94, 4
	s_and_b32 s0, s0, 0xffffff80
	s_nop 8
	v_add_u32_e32 v4, s0, v94
	s_and_b32 s0, s94, 7
	v_ashrrev_i32_e32 v5, 31, v4
	s_cmp_eq_u32 s0, 0
	v_mov_b32_e32 v6, 0
	s_cbranch_scc0 .LBB0_58
	v_or_b32_e32 v6, v4, v101
	v_readlane_b32 s36, v236, 16
	v_ashrrev_i32_e32 v7, 31, v6
	v_readlane_b32 s38, v236, 18
	v_readlane_b32 s39, v236, 19
	v_readlane_b32 s37, v236, 17
	v_readlane_b32 s40, v236, 20
	v_lshl_add_u64 v[6:7], v[6:7], 2, s[38:39]
	global_load_dword v6, v[6:7], off
	v_readlane_b32 s41, v236, 21
	v_readlane_b32 s42, v236, 22
	v_readlane_b32 s43, v236, 23
	v_readlane_b32 s44, v236, 24
	v_readlane_b32 s45, v236, 25
	v_readlane_b32 s46, v236, 26
	v_readlane_b32 s47, v236, 27
	v_readlane_b32 s48, v236, 28
	v_readlane_b32 s49, v236, 29
	v_readlane_b32 s50, v236, 30
	v_readlane_b32 s51, v236, 31
	s_branch .LBB0_58
